# hand-written weight conversion (prologue part a): register transpose with 8 dword loads + one dwordx4 store per 64x64 tile per thread, 4 tiles in flight, no LDS; replaces the instruction-bound compile
# speedup vs baseline: 1.0054x; 1.0054x over previous
.LBB0_5:
	s_or_b64 exec, exec, s[0:1]
	v_writelane_b32 v254, s4, 22
	s_add_u32 s52, s34, 0x18000000
	s_mov_b32 s0, s96
	v_writelane_b32 v254, s5, 23
	v_writelane_b32 v254, s6, 24
	v_writelane_b32 v254, s7, 25
	v_writelane_b32 v254, s8, 26
	v_writelane_b32 v254, s9, 27
	v_writelane_b32 v254, s10, 28
	v_writelane_b32 v254, s11, 29
	v_writelane_b32 v254, s12, 30
	v_writelane_b32 v254, s13, 31
	v_writelane_b32 v254, s14, 32
	v_writelane_b32 v254, s15, 33
	s_addc_u32 s53, s35, 0
	v_writelane_b32 v254, s16, 34
	v_mbcnt_lo_u32_b32 v62, -1, 0
	v_mbcnt_hi_u32_b32 v62, -1, v62
	s_cmpk_lt_i32 s2, 0x1950
	v_lshl_add_u32 v63, s0, 6, v62
	v_writelane_b32 v254, s17, 35
	v_and_b32_e32 v2, 63, v62
	v_ashrrev_i32_e32 v3, 6, v63
	s_mov_b32 s65, 0
	s_cselect_b64 s[70:71], -1, 0
	s_cmpk_gt_i32 s2, 0x194f
	s_movk_i32 s64, 0x400
	v_writelane_b32 v254, s18, 36
	v_writelane_b32 v254, s19, 37
	v_lshlrev_b32_e32 v4, 2, v2
	v_lshlrev_b32_e32 v5, 1, v2
	v_subrev_u32_e32 v6, 63, v5
	v_cmp_gt_u32_e32 vcc, 32, v2
	s_nop 1
	v_cndmask_b32_e32 v5, v6, v5, vcc
	s_mov_b32 s84, 0
.Lpa_loop:
	s_lshl_b32 s0, s84, 2
	s_mul_i32 s0, s0, s86
	s_add_u32 s3, s0, s2
	s_sub_u32 s0, s3, s86
	s_cmp_ge_u32 s3, 6480
	s_cselect_b32 s3, s0, s3
	s_sub_u32 s0, s3, s86
	s_cmp_ge_u32 s3, 6480
	s_cselect_b32 s3, s0, s3
	s_sub_u32 s0, s3, s86
	s_cmp_ge_u32 s3, 6480
	s_cselect_b32 s3, s0, s3
	s_cmp_ge_u32 s3, 5456
	s_cbranch_scc1 .Lpa_s0_j15
	s_cmp_ge_u32 s3, 4432
	s_cbranch_scc1 .Lpa_s0_j14
	s_cmp_ge_u32 s3, 3920
	s_cbranch_scc1 .Lpa_s0_j13
	s_cmp_ge_u32 s3, 3728
	s_cbranch_scc1 .Lpa_s0_j12
	s_cmp_ge_u32 s3, 3600
	s_cbranch_scc1 .Lpa_s0_j11
	s_cmp_ge_u32 s3, 3472
	s_cbranch_scc1 .Lpa_s0_j10
	s_cmp_ge_u32 s3, 3408
	s_cbranch_scc1 .Lpa_s0_j9
	s_cmp_ge_u32 s3, 3392
	s_cbranch_scc1 .Lpa_s0_j8
	s_cmp_ge_u32 s3, 3328
	s_cbranch_scc1 .Lpa_s0_j7
	s_cmp_ge_u32 s3, 2304
	s_cbranch_scc1 .Lpa_s0_j6
	s_cmp_ge_u32 s3, 1280
	s_cbranch_scc1 .Lpa_s0_j5
	s_cmp_ge_u32 s3, 1024
	s_cbranch_scc1 .Lpa_s0_j4
	s_cmp_ge_u32 s3, 768
	s_cbranch_scc1 .Lpa_s0_j3
	s_cmp_ge_u32 s3, 512
	s_cbranch_scc1 .Lpa_s0_j2
	s_cmp_ge_u32 s3, 256
	s_cbranch_scc1 .Lpa_s0_j1
	s_branch .Lpa_s0_j0
.Lpa_s0_j0:
	v_readlane_b32 s0, v254, 7
	v_readlane_b32 s1, v254, 8
	v_readlane_b32 s98, v254, 5
	v_readlane_b32 s99, v254, 6
	s_mov_b32 s28, 0
	s_mov_b32 s29, 16
	s_mov_b32 s30, 0x1000
	s_mov_b32 s67, 0x1000
	s_mov_b32 s66, 11
	s_mov_b32 s33, 0
	s_mov_b32 s97, 0x18000000
	s_mov_b32 s85, 1
	s_branch .Lpa_s0_join
.Lpa_s0_j1:
	v_readlane_b32 s0, v254, 9
	v_readlane_b32 s1, v254, 10
	v_readlane_b32 s98, v254, 5
	v_readlane_b32 s99, v254, 6
	s_mov_b32 s28, 256
	s_mov_b32 s29, 16
	s_mov_b32 s30, 0x1000
	s_mov_b32 s67, 0x1000
	s_mov_b32 s66, 11
	s_mov_b32 s33, 0
	s_mov_b32 s97, 0x18200000
	s_mov_b32 s85, 1
	s_branch .Lpa_s0_join
.Lpa_s0_j2:
	v_readlane_b32 s0, v254, 11
	v_readlane_b32 s1, v254, 12
	v_readlane_b32 s98, v254, 5
	v_readlane_b32 s99, v254, 6
	s_mov_b32 s28, 512
	s_mov_b32 s29, 16
	s_mov_b32 s30, 0x1000
	s_mov_b32 s67, 0x1000
	s_mov_b32 s66, 11
	s_mov_b32 s33, 0
	s_mov_b32 s97, 0x18600000
	s_mov_b32 s85, 1
	s_branch .Lpa_s0_join
.Lpa_s0_j3:
	v_readlane_b32 s0, v254, 13
	v_readlane_b32 s1, v254, 14
	v_readlane_b32 s98, v254, 5
	v_readlane_b32 s99, v254, 6
	s_mov_b32 s28, 768
	s_mov_b32 s29, 16
	s_mov_b32 s30, 0x1000
	s_mov_b32 s67, 0x1000
	s_mov_b32 s66, 11
	s_mov_b32 s33, 0
	s_mov_b32 s97, 0x18400000
	s_mov_b32 s85, 1
	s_branch .Lpa_s0_join
.Lpa_s0_j4:
	v_readlane_b32 s0, v254, 17
	v_readlane_b32 s1, v254, 18
	s_mov_b32 s28, 1024
	s_mov_b32 s29, 16
	s_mov_b32 s30, 0x1000
	s_mov_b32 s67, 0x1000
	s_mov_b32 s66, 11
	s_mov_b32 s33, 0
	s_mov_b32 s97, 0x18800000
	s_mov_b32 s85, 0
	s_branch .Lpa_s0_join
.Lpa_s0_j5:
	s_mov_b32 s0, s44
	s_mov_b32 s1, s45
	s_mov_b32 s98, s42
	s_mov_b32 s99, s43
	s_mov_b32 s28, 1280
	s_mov_b32 s29, 64
	s_mov_b32 s30, 0x400
	s_mov_b32 s67, 0x4000
	s_mov_b32 s66, 11
	s_mov_b32 s33, 0
	s_mov_b32 s97, 0x18a00000
	s_mov_b32 s85, 1
	s_branch .Lpa_s0_join
.Lpa_s0_j6:
	s_mov_b32 s0, s46
	s_mov_b32 s1, s47
	s_mov_b32 s28, 2304
	s_mov_b32 s29, 16
	s_mov_b32 s30, 0x1000
	s_mov_b32 s67, 0x1000
	s_mov_b32 s66, 13
	s_mov_b32 s33, 0
	s_mov_b32 s97, 0x19200000
	s_mov_b32 s85, 0
	s_branch .Lpa_s0_join
.Lpa_s0_j7:
	v_readlane_b32 s0, v254, 36
	v_readlane_b32 s1, v254, 37
	v_readlane_b32 s98, v254, 34
	v_readlane_b32 s99, v254, 35
	s_mov_b32 s28, 3328
	s_mov_b32 s29, 4
	s_mov_b32 s30, 0x4000
	s_mov_b32 s67, 0x500
	s_mov_b32 s66, 11
	s_mov_b32 s33, 0
	s_mov_b32 s97, 0x19a00000
	s_mov_b32 s85, 1
	s_branch .Lpa_s0_join
.Lpa_s0_j8:
	v_readlane_b32 s0, v254, 36
	v_readlane_b32 s1, v254, 37
	v_readlane_b32 s98, v254, 34
	v_readlane_b32 s99, v254, 35
	s_mov_b32 s28, 3392
	s_mov_b32 s29, 1
	s_mov_b32 s30, 0x10000
	s_mov_b32 s67, 0x500
	s_mov_b32 s66, 11
	s_mov_b32 s33, 1
	s_mov_b32 s97, 0x19b00000
	s_add_u32 s0, s0, 0x400
	s_addc_u32 s1, s1, 0
	s_mov_b32 s85, 1
	s_branch .Lpa_s0_join
.Lpa_s0_j9:
	v_readlane_b32 s0, v254, 26
	v_readlane_b32 s1, v254, 27
	v_readlane_b32 s98, v254, 24
	v_readlane_b32 s99, v254, 25
	s_mov_b32 s28, 3408
	s_mov_b32 s29, 4
	s_mov_b32 s30, 0x4000
	s_mov_b32 s67, 0x400
	s_mov_b32 s66, 11
	s_mov_b32 s33, 0
	s_mov_b32 s97, 0x19a80000
	s_mov_b32 s85, 1
	s_branch .Lpa_s0_join
.Lpa_s0_j10:
	s_mov_b32 s0, s38
	s_mov_b32 s1, s39
	s_mov_b32 s98, s36
	s_mov_b32 s99, s37
	s_mov_b32 s28, 3472
	s_mov_b32 s29, 32
	s_mov_b32 s30, 0x800
	s_mov_b32 s67, 0x2000
	s_mov_b32 s66, 9
	s_mov_b32 s33, 0
	s_mov_b32 s97, 0x1e400000
	s_mov_b32 s85, 1
	s_branch .Lpa_s0_join
.Lpa_s0_j11:
	s_mov_b32 s0, s40
	s_mov_b32 s1, s41
	s_mov_b32 s98, s36
	s_mov_b32 s99, s37
	s_mov_b32 s28, 3600
	s_mov_b32 s29, 32
	s_mov_b32 s30, 0x800
	s_mov_b32 s67, 0x2000
	s_mov_b32 s66, 9
	s_mov_b32 s33, 0
	s_mov_b32 s97, 0x1e500000
	s_mov_b32 s85, 1
	s_branch .Lpa_s0_join
.Lpa_s0_j12:
	v_readlane_b32 s0, v254, 30
	v_readlane_b32 s1, v254, 31
	v_readlane_b32 s98, v254, 28
	v_readlane_b32 s99, v254, 29
	s_mov_b32 s28, 3728
	s_mov_b32 s29, 48
	s_mov_b32 s30, 0x556
	s_mov_b32 s67, 0x3000
	s_mov_b32 s66, 9
	s_mov_b32 s33, 2
	s_mov_b32 s97, 0x1e600000
	s_mov_b32 s85, 1
	s_branch .Lpa_s0_join
.Lpa_s0_j13:
	v_readlane_b32 s0, v254, 32
	v_readlane_b32 s1, v254, 33
	s_mov_b32 s28, 3920
	s_mov_b32 s29, 16
	s_mov_b32 s30, 0x1000
	s_mov_b32 s67, 0x1000
	s_mov_b32 s66, 12
	s_mov_b32 s33, 0
	s_mov_b32 s97, 0x1e780000
	s_mov_b32 s85, 0
	s_branch .Lpa_s0_join
.Lpa_s0_j14:
	s_mov_b32 s0, s44
	s_mov_b32 s1, s45
	s_mov_b32 s98, s42
	s_mov_b32 s99, s43
	s_mov_b32 s28, 4432
	s_mov_b32 s29, 64
	s_mov_b32 s30, 0x400
	s_mov_b32 s67, 0x4000
	s_mov_b32 s66, 11
	s_mov_b32 s33, 0
	s_mov_b32 s97, 0x1eb80000
	s_add_u32 s0, s0, 0x1000000
	s_addc_u32 s1, s1, 0
	s_add_u32 s98, s98, 0x1000
	s_addc_u32 s99, s99, 0
	s_mov_b32 s85, 1
	s_branch .Lpa_s0_join
.Lpa_s0_j15:
	s_mov_b32 s0, s46
	s_mov_b32 s1, s47
	s_mov_b32 s28, 5456
	s_mov_b32 s29, 16
	s_mov_b32 s30, 0x1000
	s_mov_b32 s67, 0x1000
	s_mov_b32 s66, 13
	s_mov_b32 s33, 0
	s_mov_b32 s97, 0x1f380000
	s_add_u32 s0, s0, 0x1000000
	s_addc_u32 s1, s1, 0
	s_mov_b32 s85, 0
	s_branch .Lpa_s0_join
.Lpa_s0_join:
	s_nop 1
	s_sub_u32 s3, s3, s28
	s_mul_i32 s28, s3, s30
	s_lshr_b32 s28, s28, 16
	s_mul_i32 s100, s28, s29
	s_sub_u32 s3, s3, s100
	s_lshl_b32 s28, s28, 6
	s_lshl_b32 s100, s96, 3
	s_add_u32 s28, s28, s100
	s_mul_hi_u32 s100, s3, 0x55555556
	s_mul_i32 s100, s100, 3
	s_sub_u32 s100, s3, s100
	s_cmp_eq_u32 s100, 2
	s_cselect_b32 s100, 2, 1
	s_cmp_eq_u32 s33, 1
	s_cselect_b32 s100, 1, s100
	s_cmp_eq_u32 s33, s100
	s_cselect_b64 s[64:65], -1, 0
	s_mul_i32 s100, s28, s67
	s_lshl_b32 s101, s3, 8
	s_add_u32 s100, s100, s101
	s_add_u32 s60, s0, s100
	s_addc_u32 s61, s1, 0
	s_cmp_eq_u32 s85, 0
	s_cbranch_scc1 .Lpa_s0_nog
	s_lshl_b32 s100, s28, 2
	s_add_u32 s98, s98, s100
	s_addc_u32 s99, s99, 0
	s_load_dwordx8 s[4:11], s[98:99], 0x0
	s_branch .Lpa_s0_gd
.Lpa_s0_nog:
	s_mov_b32 s4, 1.0
	s_mov_b32 s5, 1.0
	s_mov_b32 s6, 1.0
	s_mov_b32 s7, 1.0
	s_mov_b32 s8, 1.0
	s_mov_b32 s9, 1.0
	s_mov_b32 s10, 1.0
	s_mov_b32 s11, 1.0
.Lpa_s0_gd:
	s_add_u32 s100, s66, 6
	s_lshl_b32 s100, s3, s100
	s_lshl_b32 s101, s28, 1
	s_add_u32 s100, s100, s101
	s_add_u32 s100, s100, s97
	s_add_u32 s62, s34, s100
	s_addc_u32 s63, s35, 0
	global_load_dword v10, v4, s[60:61]
	s_add_u32 s60, s60, s67
	s_addc_u32 s61, s61, 0
	global_load_dword v11, v4, s[60:61]
	s_add_u32 s60, s60, s67
	s_addc_u32 s61, s61, 0
	global_load_dword v12, v4, s[60:61]
	s_add_u32 s60, s60, s67
	s_addc_u32 s61, s61, 0
	global_load_dword v13, v4, s[60:61]
	s_add_u32 s60, s60, s67
	s_addc_u32 s61, s61, 0
	global_load_dword v14, v4, s[60:61]
	s_add_u32 s60, s60, s67
	s_addc_u32 s61, s61, 0
	global_load_dword v15, v4, s[60:61]
	s_add_u32 s60, s60, s67
	s_addc_u32 s61, s61, 0
	global_load_dword v16, v4, s[60:61]
	s_add_u32 s60, s60, s67
	s_addc_u32 s61, s61, 0
	global_load_dword v17, v4, s[60:61]
	s_lshl_b32 s0, s84, 2
	s_add_u32 s0, s0, 1
	s_mul_i32 s0, s0, s86
	s_add_u32 s3, s0, s2
	s_sub_u32 s0, s3, s86
	s_cmp_ge_u32 s3, 6480
	s_cselect_b32 s3, s0, s3
	s_sub_u32 s0, s3, s86
	s_cmp_ge_u32 s3, 6480
	s_cselect_b32 s3, s0, s3
	s_sub_u32 s0, s3, s86
	s_cmp_ge_u32 s3, 6480
	s_cselect_b32 s3, s0, s3
	s_cmp_ge_u32 s3, 5456
	s_cbranch_scc1 .Lpa_s1_j15
	s_cmp_ge_u32 s3, 4432
	s_cbranch_scc1 .Lpa_s1_j14
	s_cmp_ge_u32 s3, 3920
	s_cbranch_scc1 .Lpa_s1_j13
	s_cmp_ge_u32 s3, 3728
	s_cbranch_scc1 .Lpa_s1_j12
	s_cmp_ge_u32 s3, 3600
	s_cbranch_scc1 .Lpa_s1_j11
	s_cmp_ge_u32 s3, 3472
	s_cbranch_scc1 .Lpa_s1_j10
	s_cmp_ge_u32 s3, 3408
	s_cbranch_scc1 .Lpa_s1_j9
	s_cmp_ge_u32 s3, 3392
	s_cbranch_scc1 .Lpa_s1_j8
	s_cmp_ge_u32 s3, 3328
	s_cbranch_scc1 .Lpa_s1_j7
	s_cmp_ge_u32 s3, 2304
	s_cbranch_scc1 .Lpa_s1_j6
	s_cmp_ge_u32 s3, 1280
	s_cbranch_scc1 .Lpa_s1_j5
	s_cmp_ge_u32 s3, 1024
	s_cbranch_scc1 .Lpa_s1_j4
	s_cmp_ge_u32 s3, 768
	s_cbranch_scc1 .Lpa_s1_j3
	s_cmp_ge_u32 s3, 512
	s_cbranch_scc1 .Lpa_s1_j2
	s_cmp_ge_u32 s3, 256
	s_cbranch_scc1 .Lpa_s1_j1
	s_branch .Lpa_s1_j0
.Lpa_s1_j0:
	v_readlane_b32 s0, v254, 7
	v_readlane_b32 s1, v254, 8
	v_readlane_b32 s98, v254, 5
	v_readlane_b32 s99, v254, 6
	s_mov_b32 s28, 0
	s_mov_b32 s29, 16
	s_mov_b32 s30, 0x1000
	s_mov_b32 s75, 0x1000
	s_mov_b32 s74, 11
	s_mov_b32 s33, 0
	s_mov_b32 s97, 0x18000000
	s_mov_b32 s85, 1
	s_branch .Lpa_s1_join
.Lpa_s1_j1:
	v_readlane_b32 s0, v254, 9
	v_readlane_b32 s1, v254, 10
	v_readlane_b32 s98, v254, 5
	v_readlane_b32 s99, v254, 6
	s_mov_b32 s28, 256
	s_mov_b32 s29, 16
	s_mov_b32 s30, 0x1000
	s_mov_b32 s75, 0x1000
	s_mov_b32 s74, 11
	s_mov_b32 s33, 0
	s_mov_b32 s97, 0x18200000
	s_mov_b32 s85, 1
	s_branch .Lpa_s1_join
.Lpa_s1_j2:
	v_readlane_b32 s0, v254, 11
	v_readlane_b32 s1, v254, 12
	v_readlane_b32 s98, v254, 5
	v_readlane_b32 s99, v254, 6
	s_mov_b32 s28, 512
	s_mov_b32 s29, 16
	s_mov_b32 s30, 0x1000
	s_mov_b32 s75, 0x1000
	s_mov_b32 s74, 11
	s_mov_b32 s33, 0
	s_mov_b32 s97, 0x18600000
	s_mov_b32 s85, 1
	s_branch .Lpa_s1_join
.Lpa_s1_j3:
	v_readlane_b32 s0, v254, 13
	v_readlane_b32 s1, v254, 14
	v_readlane_b32 s98, v254, 5
	v_readlane_b32 s99, v254, 6
	s_mov_b32 s28, 768
	s_mov_b32 s29, 16
	s_mov_b32 s30, 0x1000
	s_mov_b32 s75, 0x1000
	s_mov_b32 s74, 11
	s_mov_b32 s33, 0
	s_mov_b32 s97, 0x18400000
	s_mov_b32 s85, 1
	s_branch .Lpa_s1_join
.Lpa_s1_j4:
	v_readlane_b32 s0, v254, 17
	v_readlane_b32 s1, v254, 18
	s_mov_b32 s28, 1024
	s_mov_b32 s29, 16
	s_mov_b32 s30, 0x1000
	s_mov_b32 s75, 0x1000
	s_mov_b32 s74, 11
	s_mov_b32 s33, 0
	s_mov_b32 s97, 0x18800000
	s_mov_b32 s85, 0
	s_branch .Lpa_s1_join
.Lpa_s1_j5:
	s_mov_b32 s0, s44
	s_mov_b32 s1, s45
	s_mov_b32 s98, s42
	s_mov_b32 s99, s43
	s_mov_b32 s28, 1280
	s_mov_b32 s29, 64
	s_mov_b32 s30, 0x400
	s_mov_b32 s75, 0x4000
	s_mov_b32 s74, 11
	s_mov_b32 s33, 0
	s_mov_b32 s97, 0x18a00000
	s_mov_b32 s85, 1
	s_branch .Lpa_s1_join
.Lpa_s1_j6:
	s_mov_b32 s0, s46
	s_mov_b32 s1, s47
	s_mov_b32 s28, 2304
	s_mov_b32 s29, 16
	s_mov_b32 s30, 0x1000
	s_mov_b32 s75, 0x1000
	s_mov_b32 s74, 13
	s_mov_b32 s33, 0
	s_mov_b32 s97, 0x19200000
	s_mov_b32 s85, 0
	s_branch .Lpa_s1_join
.Lpa_s1_j7:
	v_readlane_b32 s0, v254, 36
	v_readlane_b32 s1, v254, 37
	v_readlane_b32 s98, v254, 34
	v_readlane_b32 s99, v254, 35
	s_mov_b32 s28, 3328
	s_mov_b32 s29, 4
	s_mov_b32 s30, 0x4000
	s_mov_b32 s75, 0x500
	s_mov_b32 s74, 11
	s_mov_b32 s33, 0
	s_mov_b32 s97, 0x19a00000
	s_mov_b32 s85, 1
	s_branch .Lpa_s1_join
.Lpa_s1_j8:
	v_readlane_b32 s0, v254, 36
	v_readlane_b32 s1, v254, 37
	v_readlane_b32 s98, v254, 34
	v_readlane_b32 s99, v254, 35
	s_mov_b32 s28, 3392
	s_mov_b32 s29, 1
	s_mov_b32 s30, 0x10000
	s_mov_b32 s75, 0x500
	s_mov_b32 s74, 11
	s_mov_b32 s33, 1
	s_mov_b32 s97, 0x19b00000
	s_add_u32 s0, s0, 0x400
	s_addc_u32 s1, s1, 0
	s_mov_b32 s85, 1
	s_branch .Lpa_s1_join
.Lpa_s1_j9:
	v_readlane_b32 s0, v254, 26
	v_readlane_b32 s1, v254, 27
	v_readlane_b32 s98, v254, 24
	v_readlane_b32 s99, v254, 25
	s_mov_b32 s28, 3408
	s_mov_b32 s29, 4
	s_mov_b32 s30, 0x4000
	s_mov_b32 s75, 0x400
	s_mov_b32 s74, 11
	s_mov_b32 s33, 0
	s_mov_b32 s97, 0x19a80000
	s_mov_b32 s85, 1
	s_branch .Lpa_s1_join
.Lpa_s1_j10:
	s_mov_b32 s0, s38
	s_mov_b32 s1, s39
	s_mov_b32 s98, s36
	s_mov_b32 s99, s37
	s_mov_b32 s28, 3472
	s_mov_b32 s29, 32
	s_mov_b32 s30, 0x800
	s_mov_b32 s75, 0x2000
	s_mov_b32 s74, 9
	s_mov_b32 s33, 0
	s_mov_b32 s97, 0x1e400000
	s_mov_b32 s85, 1
	s_branch .Lpa_s1_join
.Lpa_s1_j11:
	s_mov_b32 s0, s40
	s_mov_b32 s1, s41
	s_mov_b32 s98, s36
	s_mov_b32 s99, s37
	s_mov_b32 s28, 3600
	s_mov_b32 s29, 32
	s_mov_b32 s30, 0x800
	s_mov_b32 s75, 0x2000
	s_mov_b32 s74, 9
	s_mov_b32 s33, 0
	s_mov_b32 s97, 0x1e500000
	s_mov_b32 s85, 1
	s_branch .Lpa_s1_join
.Lpa_s1_j12:
	v_readlane_b32 s0, v254, 30
	v_readlane_b32 s1, v254, 31
	v_readlane_b32 s98, v254, 28
	v_readlane_b32 s99, v254, 29
	s_mov_b32 s28, 3728
	s_mov_b32 s29, 48
	s_mov_b32 s30, 0x556
	s_mov_b32 s75, 0x3000
	s_mov_b32 s74, 9
	s_mov_b32 s33, 2
	s_mov_b32 s97, 0x1e600000
	s_mov_b32 s85, 1
	s_branch .Lpa_s1_join
.Lpa_s1_j13:
	v_readlane_b32 s0, v254, 32
	v_readlane_b32 s1, v254, 33
	s_mov_b32 s28, 3920
	s_mov_b32 s29, 16
	s_mov_b32 s30, 0x1000
	s_mov_b32 s75, 0x1000
	s_mov_b32 s74, 12
	s_mov_b32 s33, 0
	s_mov_b32 s97, 0x1e780000
	s_mov_b32 s85, 0
	s_branch .Lpa_s1_join
.Lpa_s1_j14:
	s_mov_b32 s0, s44
	s_mov_b32 s1, s45
	s_mov_b32 s98, s42
	s_mov_b32 s99, s43
	s_mov_b32 s28, 4432
	s_mov_b32 s29, 64
	s_mov_b32 s30, 0x400
	s_mov_b32 s75, 0x4000
	s_mov_b32 s74, 11
	s_mov_b32 s33, 0
	s_mov_b32 s97, 0x1eb80000
	s_add_u32 s0, s0, 0x1000000
	s_addc_u32 s1, s1, 0
	s_add_u32 s98, s98, 0x1000
	s_addc_u32 s99, s99, 0
	s_mov_b32 s85, 1
	s_branch .Lpa_s1_join
.Lpa_s1_j15:
	s_mov_b32 s0, s46
	s_mov_b32 s1, s47
	s_mov_b32 s28, 5456
	s_mov_b32 s29, 16
	s_mov_b32 s30, 0x1000
	s_mov_b32 s75, 0x1000
	s_mov_b32 s74, 13
	s_mov_b32 s33, 0
	s_mov_b32 s97, 0x1f380000
	s_add_u32 s0, s0, 0x1000000
	s_addc_u32 s1, s1, 0
	s_mov_b32 s85, 0
	s_branch .Lpa_s1_join
.Lpa_s1_join:
	s_nop 1
	s_sub_u32 s3, s3, s28
	s_mul_i32 s28, s3, s30
	s_lshr_b32 s28, s28, 16
	s_mul_i32 s100, s28, s29
	s_sub_u32 s3, s3, s100
	s_lshl_b32 s28, s28, 6
	s_lshl_b32 s100, s96, 3
	s_add_u32 s28, s28, s100
	s_mul_hi_u32 s100, s3, 0x55555556
	s_mul_i32 s100, s100, 3
	s_sub_u32 s100, s3, s100
	s_cmp_eq_u32 s100, 2
	s_cselect_b32 s100, 2, 1
	s_cmp_eq_u32 s33, 1
	s_cselect_b32 s100, 1, s100
	s_cmp_eq_u32 s33, s100
	s_cselect_b64 s[72:73], -1, 0
	s_mul_i32 s100, s28, s75
	s_lshl_b32 s101, s3, 8
	s_add_u32 s100, s100, s101
	s_add_u32 s68, s0, s100
	s_addc_u32 s69, s1, 0
	s_cmp_eq_u32 s85, 0
	s_cbranch_scc1 .Lpa_s1_nog
	s_lshl_b32 s100, s28, 2
	s_add_u32 s98, s98, s100
	s_addc_u32 s99, s99, 0
	s_load_dwordx8 s[12:19], s[98:99], 0x0
	s_branch .Lpa_s1_gd
.Lpa_s1_nog:
	s_mov_b32 s12, 1.0
	s_mov_b32 s13, 1.0
	s_mov_b32 s14, 1.0
	s_mov_b32 s15, 1.0
	s_mov_b32 s16, 1.0
	s_mov_b32 s17, 1.0
	s_mov_b32 s18, 1.0
	s_mov_b32 s19, 1.0
.Lpa_s1_gd:
	s_add_u32 s100, s74, 6
	s_lshl_b32 s100, s3, s100
	s_lshl_b32 s101, s28, 1
	s_add_u32 s100, s100, s101
	s_add_u32 s100, s100, s97
	s_add_u32 s70, s34, s100
	s_addc_u32 s71, s35, 0
	global_load_dword v18, v4, s[68:69]
	s_add_u32 s68, s68, s75
	s_addc_u32 s69, s69, 0
	global_load_dword v19, v4, s[68:69]
	s_add_u32 s68, s68, s75
	s_addc_u32 s69, s69, 0
	global_load_dword v20, v4, s[68:69]
	s_add_u32 s68, s68, s75
	s_addc_u32 s69, s69, 0
	global_load_dword v21, v4, s[68:69]
	s_add_u32 s68, s68, s75
	s_addc_u32 s69, s69, 0
	global_load_dword v22, v4, s[68:69]
	s_add_u32 s68, s68, s75
	s_addc_u32 s69, s69, 0
	global_load_dword v23, v4, s[68:69]
	s_add_u32 s68, s68, s75
	s_addc_u32 s69, s69, 0
	global_load_dword v24, v4, s[68:69]
	s_add_u32 s68, s68, s75
	s_addc_u32 s69, s69, 0
	global_load_dword v25, v4, s[68:69]
	s_lshl_b32 s0, s84, 2
	s_add_u32 s0, s0, 2
	s_mul_i32 s0, s0, s86
	s_add_u32 s3, s0, s2
	s_sub_u32 s0, s3, s86
	s_cmp_ge_u32 s3, 6480
	s_cselect_b32 s3, s0, s3
	s_sub_u32 s0, s3, s86
	s_cmp_ge_u32 s3, 6480
	s_cselect_b32 s3, s0, s3
	s_sub_u32 s0, s3, s86
	s_cmp_ge_u32 s3, 6480
	s_cselect_b32 s3, s0, s3
	s_cmp_ge_u32 s3, 5456
	s_cbranch_scc1 .Lpa_s2_j15
	s_cmp_ge_u32 s3, 4432
	s_cbranch_scc1 .Lpa_s2_j14
	s_cmp_ge_u32 s3, 3920
	s_cbranch_scc1 .Lpa_s2_j13
	s_cmp_ge_u32 s3, 3728
	s_cbranch_scc1 .Lpa_s2_j12
	s_cmp_ge_u32 s3, 3600
	s_cbranch_scc1 .Lpa_s2_j11
	s_cmp_ge_u32 s3, 3472
	s_cbranch_scc1 .Lpa_s2_j10
	s_cmp_ge_u32 s3, 3408
	s_cbranch_scc1 .Lpa_s2_j9
	s_cmp_ge_u32 s3, 3392
	s_cbranch_scc1 .Lpa_s2_j8
	s_cmp_ge_u32 s3, 3328
	s_cbranch_scc1 .Lpa_s2_j7
	s_cmp_ge_u32 s3, 2304
	s_cbranch_scc1 .Lpa_s2_j6
	s_cmp_ge_u32 s3, 1280
	s_cbranch_scc1 .Lpa_s2_j5
	s_cmp_ge_u32 s3, 1024
	s_cbranch_scc1 .Lpa_s2_j4
	s_cmp_ge_u32 s3, 768
	s_cbranch_scc1 .Lpa_s2_j3
	s_cmp_ge_u32 s3, 512
	s_cbranch_scc1 .Lpa_s2_j2
	s_cmp_ge_u32 s3, 256
	s_cbranch_scc1 .Lpa_s2_j1
	s_branch .Lpa_s2_j0
.Lpa_s2_j0:
	v_readlane_b32 s0, v254, 7
	v_readlane_b32 s1, v254, 8
	v_readlane_b32 s98, v254, 5
	v_readlane_b32 s99, v254, 6
	s_mov_b32 s28, 0
	s_mov_b32 s29, 16
	s_mov_b32 s30, 0x1000
	s_mov_b32 s83, 0x1000
	s_mov_b32 s82, 11
	s_mov_b32 s33, 0
	s_mov_b32 s97, 0x18000000
	s_mov_b32 s85, 1
	s_branch .Lpa_s2_join
.Lpa_s2_j1:
	v_readlane_b32 s0, v254, 9
	v_readlane_b32 s1, v254, 10
	v_readlane_b32 s98, v254, 5
	v_readlane_b32 s99, v254, 6
	s_mov_b32 s28, 256
	s_mov_b32 s29, 16
	s_mov_b32 s30, 0x1000
	s_mov_b32 s83, 0x1000
	s_mov_b32 s82, 11
	s_mov_b32 s33, 0
	s_mov_b32 s97, 0x18200000
	s_mov_b32 s85, 1
	s_branch .Lpa_s2_join
.Lpa_s2_j2:
	v_readlane_b32 s0, v254, 11
	v_readlane_b32 s1, v254, 12
	v_readlane_b32 s98, v254, 5
	v_readlane_b32 s99, v254, 6
	s_mov_b32 s28, 512
	s_mov_b32 s29, 16
	s_mov_b32 s30, 0x1000
	s_mov_b32 s83, 0x1000
	s_mov_b32 s82, 11
	s_mov_b32 s33, 0
	s_mov_b32 s97, 0x18600000
	s_mov_b32 s85, 1
	s_branch .Lpa_s2_join
.Lpa_s2_j3:
	v_readlane_b32 s0, v254, 13
	v_readlane_b32 s1, v254, 14
	v_readlane_b32 s98, v254, 5
	v_readlane_b32 s99, v254, 6
	s_mov_b32 s28, 768
	s_mov_b32 s29, 16
	s_mov_b32 s30, 0x1000
	s_mov_b32 s83, 0x1000
	s_mov_b32 s82, 11
	s_mov_b32 s33, 0
	s_mov_b32 s97, 0x18400000
	s_mov_b32 s85, 1
	s_branch .Lpa_s2_join
.Lpa_s2_j4:
	v_readlane_b32 s0, v254, 17
	v_readlane_b32 s1, v254, 18
	s_mov_b32 s28, 1024
	s_mov_b32 s29, 16
	s_mov_b32 s30, 0x1000
	s_mov_b32 s83, 0x1000
	s_mov_b32 s82, 11
	s_mov_b32 s33, 0
	s_mov_b32 s97, 0x18800000
	s_mov_b32 s85, 0
	s_branch .Lpa_s2_join
.Lpa_s2_j5:
	s_mov_b32 s0, s44
	s_mov_b32 s1, s45
	s_mov_b32 s98, s42
	s_mov_b32 s99, s43
	s_mov_b32 s28, 1280
	s_mov_b32 s29, 64
	s_mov_b32 s30, 0x400
	s_mov_b32 s83, 0x4000
	s_mov_b32 s82, 11
	s_mov_b32 s33, 0
	s_mov_b32 s97, 0x18a00000
	s_mov_b32 s85, 1
	s_branch .Lpa_s2_join
.Lpa_s2_j6:
	s_mov_b32 s0, s46
	s_mov_b32 s1, s47
	s_mov_b32 s28, 2304
	s_mov_b32 s29, 16
	s_mov_b32 s30, 0x1000
	s_mov_b32 s83, 0x1000
	s_mov_b32 s82, 13
	s_mov_b32 s33, 0
	s_mov_b32 s97, 0x19200000
	s_mov_b32 s85, 0
	s_branch .Lpa_s2_join
.Lpa_s2_j7:
	v_readlane_b32 s0, v254, 36
	v_readlane_b32 s1, v254, 37
	v_readlane_b32 s98, v254, 34
	v_readlane_b32 s99, v254, 35
	s_mov_b32 s28, 3328
	s_mov_b32 s29, 4
	s_mov_b32 s30, 0x4000
	s_mov_b32 s83, 0x500
	s_mov_b32 s82, 11
	s_mov_b32 s33, 0
	s_mov_b32 s97, 0x19a00000
	s_mov_b32 s85, 1
	s_branch .Lpa_s2_join
.Lpa_s2_j8:
	v_readlane_b32 s0, v254, 36
	v_readlane_b32 s1, v254, 37
	v_readlane_b32 s98, v254, 34
	v_readlane_b32 s99, v254, 35
	s_mov_b32 s28, 3392
	s_mov_b32 s29, 1
	s_mov_b32 s30, 0x10000
	s_mov_b32 s83, 0x500
	s_mov_b32 s82, 11
	s_mov_b32 s33, 1
	s_mov_b32 s97, 0x19b00000
	s_add_u32 s0, s0, 0x400
	s_addc_u32 s1, s1, 0
	s_mov_b32 s85, 1
	s_branch .Lpa_s2_join
.Lpa_s2_j9:
	v_readlane_b32 s0, v254, 26
	v_readlane_b32 s1, v254, 27
	v_readlane_b32 s98, v254, 24
	v_readlane_b32 s99, v254, 25
	s_mov_b32 s28, 3408
	s_mov_b32 s29, 4
	s_mov_b32 s30, 0x4000
	s_mov_b32 s83, 0x400
	s_mov_b32 s82, 11
	s_mov_b32 s33, 0
	s_mov_b32 s97, 0x19a80000
	s_mov_b32 s85, 1
	s_branch .Lpa_s2_join
.Lpa_s2_j10:
	s_mov_b32 s0, s38
	s_mov_b32 s1, s39
	s_mov_b32 s98, s36
	s_mov_b32 s99, s37
	s_mov_b32 s28, 3472
	s_mov_b32 s29, 32
	s_mov_b32 s30, 0x800
	s_mov_b32 s83, 0x2000
	s_mov_b32 s82, 9
	s_mov_b32 s33, 0
	s_mov_b32 s97, 0x1e400000
	s_mov_b32 s85, 1
	s_branch .Lpa_s2_join
.Lpa_s2_j11:
	s_mov_b32 s0, s40
	s_mov_b32 s1, s41
	s_mov_b32 s98, s36
	s_mov_b32 s99, s37
	s_mov_b32 s28, 3600
	s_mov_b32 s29, 32
	s_mov_b32 s30, 0x800
	s_mov_b32 s83, 0x2000
	s_mov_b32 s82, 9
	s_mov_b32 s33, 0
	s_mov_b32 s97, 0x1e500000
	s_mov_b32 s85, 1
	s_branch .Lpa_s2_join
.Lpa_s2_j12:
	v_readlane_b32 s0, v254, 30
	v_readlane_b32 s1, v254, 31
	v_readlane_b32 s98, v254, 28
	v_readlane_b32 s99, v254, 29
	s_mov_b32 s28, 3728
	s_mov_b32 s29, 48
	s_mov_b32 s30, 0x556
	s_mov_b32 s83, 0x3000
	s_mov_b32 s82, 9
	s_mov_b32 s33, 2
	s_mov_b32 s97, 0x1e600000
	s_mov_b32 s85, 1
	s_branch .Lpa_s2_join
.Lpa_s2_j13:
	v_readlane_b32 s0, v254, 32
	v_readlane_b32 s1, v254, 33
	s_mov_b32 s28, 3920
	s_mov_b32 s29, 16
	s_mov_b32 s30, 0x1000
	s_mov_b32 s83, 0x1000
	s_mov_b32 s82, 12
	s_mov_b32 s33, 0
	s_mov_b32 s97, 0x1e780000
	s_mov_b32 s85, 0
	s_branch .Lpa_s2_join
.Lpa_s2_j14:
	s_mov_b32 s0, s44
	s_mov_b32 s1, s45
	s_mov_b32 s98, s42
	s_mov_b32 s99, s43
	s_mov_b32 s28, 4432
	s_mov_b32 s29, 64
	s_mov_b32 s30, 0x400
	s_mov_b32 s83, 0x4000
	s_mov_b32 s82, 11
	s_mov_b32 s33, 0
	s_mov_b32 s97, 0x1eb80000
	s_add_u32 s0, s0, 0x1000000
	s_addc_u32 s1, s1, 0
	s_add_u32 s98, s98, 0x1000
	s_addc_u32 s99, s99, 0
	s_mov_b32 s85, 1
	s_branch .Lpa_s2_join
.Lpa_s2_j15:
	s_mov_b32 s0, s46
	s_mov_b32 s1, s47
	s_mov_b32 s28, 5456
	s_mov_b32 s29, 16
	s_mov_b32 s30, 0x1000
	s_mov_b32 s83, 0x1000
	s_mov_b32 s82, 13
	s_mov_b32 s33, 0
	s_mov_b32 s97, 0x1f380000
	s_add_u32 s0, s0, 0x1000000
	s_addc_u32 s1, s1, 0
	s_mov_b32 s85, 0
	s_branch .Lpa_s2_join
.Lpa_s2_join:
	s_nop 1
	s_sub_u32 s3, s3, s28
	s_mul_i32 s28, s3, s30
	s_lshr_b32 s28, s28, 16
	s_mul_i32 s100, s28, s29
	s_sub_u32 s3, s3, s100
	s_lshl_b32 s28, s28, 6
	s_lshl_b32 s100, s96, 3
	s_add_u32 s28, s28, s100
	s_mul_hi_u32 s100, s3, 0x55555556
	s_mul_i32 s100, s100, 3
	s_sub_u32 s100, s3, s100
	s_cmp_eq_u32 s100, 2
	s_cselect_b32 s100, 2, 1
	s_cmp_eq_u32 s33, 1
	s_cselect_b32 s100, 1, s100
	s_cmp_eq_u32 s33, s100
	s_cselect_b64 s[80:81], -1, 0
	s_mul_i32 s100, s28, s83
	s_lshl_b32 s101, s3, 8
	s_add_u32 s100, s100, s101
	s_add_u32 s76, s0, s100
	s_addc_u32 s77, s1, 0
	s_cmp_eq_u32 s85, 0
	s_cbranch_scc1 .Lpa_s2_nog
	s_lshl_b32 s100, s28, 2
	s_add_u32 s98, s98, s100
	s_addc_u32 s99, s99, 0
	s_load_dwordx8 s[20:27], s[98:99], 0x0
	s_branch .Lpa_s2_gd
.Lpa_s2_nog:
	s_mov_b32 s20, 1.0
	s_mov_b32 s21, 1.0
	s_mov_b32 s22, 1.0
	s_mov_b32 s23, 1.0
	s_mov_b32 s24, 1.0
	s_mov_b32 s25, 1.0
	s_mov_b32 s26, 1.0
	s_mov_b32 s27, 1.0
.Lpa_s2_gd:
	s_add_u32 s100, s82, 6
	s_lshl_b32 s100, s3, s100
	s_lshl_b32 s101, s28, 1
	s_add_u32 s100, s100, s101
	s_add_u32 s100, s100, s97
	s_add_u32 s78, s34, s100
	s_addc_u32 s79, s35, 0
	global_load_dword v26, v4, s[76:77]
	s_add_u32 s76, s76, s83
	s_addc_u32 s77, s77, 0
	global_load_dword v27, v4, s[76:77]
	s_add_u32 s76, s76, s83
	s_addc_u32 s77, s77, 0
	global_load_dword v28, v4, s[76:77]
	s_add_u32 s76, s76, s83
	s_addc_u32 s77, s77, 0
	global_load_dword v29, v4, s[76:77]
	s_add_u32 s76, s76, s83
	s_addc_u32 s77, s77, 0
	global_load_dword v30, v4, s[76:77]
	s_add_u32 s76, s76, s83
	s_addc_u32 s77, s77, 0
	global_load_dword v31, v4, s[76:77]
	s_add_u32 s76, s76, s83
	s_addc_u32 s77, s77, 0
	global_load_dword v32, v4, s[76:77]
	s_add_u32 s76, s76, s83
	s_addc_u32 s77, s77, 0
	global_load_dword v33, v4, s[76:77]
	s_lshl_b32 s0, s84, 2
	s_add_u32 s0, s0, 3
	s_mul_i32 s0, s0, s86
	s_add_u32 s3, s0, s2
	s_sub_u32 s0, s3, s86
	s_cmp_ge_u32 s3, 6480
	s_cselect_b32 s3, s0, s3
	s_sub_u32 s0, s3, s86
	s_cmp_ge_u32 s3, 6480
	s_cselect_b32 s3, s0, s3
	s_sub_u32 s0, s3, s86
	s_cmp_ge_u32 s3, 6480
	s_cselect_b32 s3, s0, s3
	s_cmp_ge_u32 s3, 5456
	s_cbranch_scc1 .Lpa_s3_j15
	s_cmp_ge_u32 s3, 4432
	s_cbranch_scc1 .Lpa_s3_j14
	s_cmp_ge_u32 s3, 3920
	s_cbranch_scc1 .Lpa_s3_j13
	s_cmp_ge_u32 s3, 3728
	s_cbranch_scc1 .Lpa_s3_j12
	s_cmp_ge_u32 s3, 3600
	s_cbranch_scc1 .Lpa_s3_j11
	s_cmp_ge_u32 s3, 3472
	s_cbranch_scc1 .Lpa_s3_j10
	s_cmp_ge_u32 s3, 3408
	s_cbranch_scc1 .Lpa_s3_j9
	s_cmp_ge_u32 s3, 3392
	s_cbranch_scc1 .Lpa_s3_j8
	s_cmp_ge_u32 s3, 3328
	s_cbranch_scc1 .Lpa_s3_j7
	s_cmp_ge_u32 s3, 2304
	s_cbranch_scc1 .Lpa_s3_j6
	s_cmp_ge_u32 s3, 1280
	s_cbranch_scc1 .Lpa_s3_j5
	s_cmp_ge_u32 s3, 1024
	s_cbranch_scc1 .Lpa_s3_j4
	s_cmp_ge_u32 s3, 768
	s_cbranch_scc1 .Lpa_s3_j3
	s_cmp_ge_u32 s3, 512
	s_cbranch_scc1 .Lpa_s3_j2
	s_cmp_ge_u32 s3, 256
	s_cbranch_scc1 .Lpa_s3_j1
	s_branch .Lpa_s3_j0
.Lpa_s3_j0:
	v_readlane_b32 s0, v254, 7
	v_readlane_b32 s1, v254, 8
	v_readlane_b32 s98, v254, 5
	v_readlane_b32 s99, v254, 6
	s_mov_b32 s28, 0
	s_mov_b32 s29, 16
	s_mov_b32 s30, 0x1000
	s_mov_b32 s95, 0x1000
	s_mov_b32 s94, 11
	s_mov_b32 s33, 0
	s_mov_b32 s97, 0x18000000
	s_mov_b32 s85, 1
	s_branch .Lpa_s3_join
.Lpa_s3_j1:
	v_readlane_b32 s0, v254, 9
	v_readlane_b32 s1, v254, 10
	v_readlane_b32 s98, v254, 5
	v_readlane_b32 s99, v254, 6
	s_mov_b32 s28, 256
	s_mov_b32 s29, 16
	s_mov_b32 s30, 0x1000
	s_mov_b32 s95, 0x1000
	s_mov_b32 s94, 11
	s_mov_b32 s33, 0
	s_mov_b32 s97, 0x18200000
	s_mov_b32 s85, 1
	s_branch .Lpa_s3_join
.Lpa_s3_j2:
	v_readlane_b32 s0, v254, 11
	v_readlane_b32 s1, v254, 12
	v_readlane_b32 s98, v254, 5
	v_readlane_b32 s99, v254, 6
	s_mov_b32 s28, 512
	s_mov_b32 s29, 16
	s_mov_b32 s30, 0x1000
	s_mov_b32 s95, 0x1000
	s_mov_b32 s94, 11
	s_mov_b32 s33, 0
	s_mov_b32 s97, 0x18600000
	s_mov_b32 s85, 1
	s_branch .Lpa_s3_join
.Lpa_s3_j3:
	v_readlane_b32 s0, v254, 13
	v_readlane_b32 s1, v254, 14
	v_readlane_b32 s98, v254, 5
	v_readlane_b32 s99, v254, 6
	s_mov_b32 s28, 768
	s_mov_b32 s29, 16
	s_mov_b32 s30, 0x1000
	s_mov_b32 s95, 0x1000
	s_mov_b32 s94, 11
	s_mov_b32 s33, 0
	s_mov_b32 s97, 0x18400000
	s_mov_b32 s85, 1
	s_branch .Lpa_s3_join
.Lpa_s3_j4:
	v_readlane_b32 s0, v254, 17
	v_readlane_b32 s1, v254, 18
	s_mov_b32 s28, 1024
	s_mov_b32 s29, 16
	s_mov_b32 s30, 0x1000
	s_mov_b32 s95, 0x1000
	s_mov_b32 s94, 11
	s_mov_b32 s33, 0
	s_mov_b32 s97, 0x18800000
	s_mov_b32 s85, 0
	s_branch .Lpa_s3_join
.Lpa_s3_j5:
	s_mov_b32 s0, s44
	s_mov_b32 s1, s45
	s_mov_b32 s98, s42
	s_mov_b32 s99, s43
	s_mov_b32 s28, 1280
	s_mov_b32 s29, 64
	s_mov_b32 s30, 0x400
	s_mov_b32 s95, 0x4000
	s_mov_b32 s94, 11
	s_mov_b32 s33, 0
	s_mov_b32 s97, 0x18a00000
	s_mov_b32 s85, 1
	s_branch .Lpa_s3_join
.Lpa_s3_j6:
	s_mov_b32 s0, s46
	s_mov_b32 s1, s47
	s_mov_b32 s28, 2304
	s_mov_b32 s29, 16
	s_mov_b32 s30, 0x1000
	s_mov_b32 s95, 0x1000
	s_mov_b32 s94, 13
	s_mov_b32 s33, 0
	s_mov_b32 s97, 0x19200000
	s_mov_b32 s85, 0
	s_branch .Lpa_s3_join
.Lpa_s3_j7:
	v_readlane_b32 s0, v254, 36
	v_readlane_b32 s1, v254, 37
	v_readlane_b32 s98, v254, 34
	v_readlane_b32 s99, v254, 35
	s_mov_b32 s28, 3328
	s_mov_b32 s29, 4
	s_mov_b32 s30, 0x4000
	s_mov_b32 s95, 0x500
	s_mov_b32 s94, 11
	s_mov_b32 s33, 0
	s_mov_b32 s97, 0x19a00000
	s_mov_b32 s85, 1
	s_branch .Lpa_s3_join
.Lpa_s3_j8:
	v_readlane_b32 s0, v254, 36
	v_readlane_b32 s1, v254, 37
	v_readlane_b32 s98, v254, 34
	v_readlane_b32 s99, v254, 35
	s_mov_b32 s28, 3392
	s_mov_b32 s29, 1
	s_mov_b32 s30, 0x10000
	s_mov_b32 s95, 0x500
	s_mov_b32 s94, 11
	s_mov_b32 s33, 1
	s_mov_b32 s97, 0x19b00000
	s_add_u32 s0, s0, 0x400
	s_addc_u32 s1, s1, 0
	s_mov_b32 s85, 1
	s_branch .Lpa_s3_join
.Lpa_s3_j9:
	v_readlane_b32 s0, v254, 26
	v_readlane_b32 s1, v254, 27
	v_readlane_b32 s98, v254, 24
	v_readlane_b32 s99, v254, 25
	s_mov_b32 s28, 3408
	s_mov_b32 s29, 4
	s_mov_b32 s30, 0x4000
	s_mov_b32 s95, 0x400
	s_mov_b32 s94, 11
	s_mov_b32 s33, 0
	s_mov_b32 s97, 0x19a80000
	s_mov_b32 s85, 1
	s_branch .Lpa_s3_join
.Lpa_s3_j10:
	s_mov_b32 s0, s38
	s_mov_b32 s1, s39
	s_mov_b32 s98, s36
	s_mov_b32 s99, s37
	s_mov_b32 s28, 3472
	s_mov_b32 s29, 32
	s_mov_b32 s30, 0x800
	s_mov_b32 s95, 0x2000
	s_mov_b32 s94, 9
	s_mov_b32 s33, 0
	s_mov_b32 s97, 0x1e400000
	s_mov_b32 s85, 1
	s_branch .Lpa_s3_join
.Lpa_s3_j11:
	s_mov_b32 s0, s40
	s_mov_b32 s1, s41
	s_mov_b32 s98, s36
	s_mov_b32 s99, s37
	s_mov_b32 s28, 3600
	s_mov_b32 s29, 32
	s_mov_b32 s30, 0x800
	s_mov_b32 s95, 0x2000
	s_mov_b32 s94, 9
	s_mov_b32 s33, 0
	s_mov_b32 s97, 0x1e500000
	s_mov_b32 s85, 1
	s_branch .Lpa_s3_join
.Lpa_s3_j12:
	v_readlane_b32 s0, v254, 30
	v_readlane_b32 s1, v254, 31
	v_readlane_b32 s98, v254, 28
	v_readlane_b32 s99, v254, 29
	s_mov_b32 s28, 3728
	s_mov_b32 s29, 48
	s_mov_b32 s30, 0x556
	s_mov_b32 s95, 0x3000
	s_mov_b32 s94, 9
	s_mov_b32 s33, 2
	s_mov_b32 s97, 0x1e600000
	s_mov_b32 s85, 1
	s_branch .Lpa_s3_join
.Lpa_s3_j13:
	v_readlane_b32 s0, v254, 32
	v_readlane_b32 s1, v254, 33
	s_mov_b32 s28, 3920
	s_mov_b32 s29, 16
	s_mov_b32 s30, 0x1000
	s_mov_b32 s95, 0x1000
	s_mov_b32 s94, 12
	s_mov_b32 s33, 0
	s_mov_b32 s97, 0x1e780000
	s_mov_b32 s85, 0
	s_branch .Lpa_s3_join
.Lpa_s3_j14:
	s_mov_b32 s0, s44
	s_mov_b32 s1, s45
	s_mov_b32 s98, s42
	s_mov_b32 s99, s43
	s_mov_b32 s28, 4432
	s_mov_b32 s29, 64
	s_mov_b32 s30, 0x400
	s_mov_b32 s95, 0x4000
	s_mov_b32 s94, 11
	s_mov_b32 s33, 0
	s_mov_b32 s97, 0x1eb80000
	s_add_u32 s0, s0, 0x1000000
	s_addc_u32 s1, s1, 0
	s_add_u32 s98, s98, 0x1000
	s_addc_u32 s99, s99, 0
	s_mov_b32 s85, 1
	s_branch .Lpa_s3_join
.Lpa_s3_j15:
	s_mov_b32 s0, s46
	s_mov_b32 s1, s47
	s_mov_b32 s28, 5456
	s_mov_b32 s29, 16
	s_mov_b32 s30, 0x1000
	s_mov_b32 s95, 0x1000
	s_mov_b32 s94, 13
	s_mov_b32 s33, 0
	s_mov_b32 s97, 0x1f380000
	s_add_u32 s0, s0, 0x1000000
	s_addc_u32 s1, s1, 0
	s_mov_b32 s85, 0
	s_branch .Lpa_s3_join
.Lpa_s3_join:
	s_nop 1
	s_sub_u32 s3, s3, s28
	s_mul_i32 s28, s3, s30
	s_lshr_b32 s28, s28, 16
	s_mul_i32 s100, s28, s29
	s_sub_u32 s3, s3, s100
	s_lshl_b32 s28, s28, 6
	s_lshl_b32 s100, s96, 3
	s_add_u32 s28, s28, s100
	s_mul_hi_u32 s100, s3, 0x55555556
	s_mul_i32 s100, s100, 3
	s_sub_u32 s100, s3, s100
	s_cmp_eq_u32 s100, 2
	s_cselect_b32 s100, 2, 1
	s_cmp_eq_u32 s33, 1
	s_cselect_b32 s100, 1, s100
	s_cmp_eq_u32 s33, s100
	s_cselect_b64 s[92:93], -1, 0
	s_mul_i32 s100, s28, s95
	s_lshl_b32 s101, s3, 8
	s_add_u32 s100, s100, s101
	s_add_u32 s88, s0, s100
	s_addc_u32 s89, s1, 0
	s_cmp_eq_u32 s85, 0
	s_cbranch_scc1 .Lpa_s3_nog
	s_lshl_b32 s100, s28, 2
	s_add_u32 s98, s98, s100
	s_addc_u32 s99, s99, 0
	s_load_dwordx8 s[52:59], s[98:99], 0x0
	s_branch .Lpa_s3_gd
.Lpa_s3_nog:
	s_mov_b32 s52, 1.0
	s_mov_b32 s53, 1.0
	s_mov_b32 s54, 1.0
	s_mov_b32 s55, 1.0
	s_mov_b32 s56, 1.0
	s_mov_b32 s57, 1.0
	s_mov_b32 s58, 1.0
	s_mov_b32 s59, 1.0
.Lpa_s3_gd:
	s_add_u32 s100, s94, 6
	s_lshl_b32 s100, s3, s100
	s_lshl_b32 s101, s28, 1
	s_add_u32 s100, s100, s101
	s_add_u32 s100, s100, s97
	s_add_u32 s90, s34, s100
	s_addc_u32 s91, s35, 0
	global_load_dword v34, v4, s[88:89]
	s_add_u32 s88, s88, s95
	s_addc_u32 s89, s89, 0
	global_load_dword v35, v4, s[88:89]
	s_add_u32 s88, s88, s95
	s_addc_u32 s89, s89, 0
	global_load_dword v36, v4, s[88:89]
	s_add_u32 s88, s88, s95
	s_addc_u32 s89, s89, 0
	global_load_dword v37, v4, s[88:89]
	s_add_u32 s88, s88, s95
	s_addc_u32 s89, s89, 0
	global_load_dword v38, v4, s[88:89]
	s_add_u32 s88, s88, s95
	s_addc_u32 s89, s89, 0
	global_load_dword v39, v4, s[88:89]
	s_add_u32 s88, s88, s95
	s_addc_u32 s89, s89, 0
	global_load_dword v40, v4, s[88:89]
	s_add_u32 s88, s88, s95
	s_addc_u32 s89, s89, 0
	global_load_dword v41, v4, s[88:89]
	s_waitcnt lgkmcnt(0)
	s_waitcnt vmcnt(24)
	v_mul_f32_e32 v10, s4, v10
	v_mul_f32_e32 v11, s5, v11
	v_mul_f32_e32 v12, s6, v12
	v_mul_f32_e32 v13, s7, v13
	v_mul_f32_e32 v14, s8, v14
	v_mul_f32_e32 v15, s9, v15
	v_mul_f32_e32 v16, s10, v16
	v_mul_f32_e32 v17, s11, v17
	v_cvt_pk_bf16_f32 v44, v10, v11
	v_cvt_pk_bf16_f32 v45, v12, v13
	v_cvt_pk_bf16_f32 v46, v14, v15
	v_cvt_pk_bf16_f32 v47, v16, v17
	v_cndmask_b32_e64 v7, v2, v5, s[64:65]
	v_lshlrev_b32_e32 v7, s66, v7
	global_store_dwordx4 v7, v[44:47], s[62:63]
	s_waitcnt vmcnt(17)
	v_mul_f32_e32 v18, s12, v18
	v_mul_f32_e32 v19, s13, v19
	v_mul_f32_e32 v20, s14, v20
	v_mul_f32_e32 v21, s15, v21
	v_mul_f32_e32 v22, s16, v22
	v_mul_f32_e32 v23, s17, v23
	v_mul_f32_e32 v24, s18, v24
	v_mul_f32_e32 v25, s19, v25
	v_cvt_pk_bf16_f32 v48, v18, v19
	v_cvt_pk_bf16_f32 v49, v20, v21
	v_cvt_pk_bf16_f32 v50, v22, v23
	v_cvt_pk_bf16_f32 v51, v24, v25
	v_cndmask_b32_e64 v7, v2, v5, s[72:73]
	v_lshlrev_b32_e32 v7, s74, v7
	global_store_dwordx4 v7, v[48:51], s[70:71]
	s_waitcnt vmcnt(10)
	v_mul_f32_e32 v26, s20, v26
	v_mul_f32_e32 v27, s21, v27
	v_mul_f32_e32 v28, s22, v28
	v_mul_f32_e32 v29, s23, v29
	v_mul_f32_e32 v30, s24, v30
	v_mul_f32_e32 v31, s25, v31
	v_mul_f32_e32 v32, s26, v32
	v_mul_f32_e32 v33, s27, v33
	v_cvt_pk_bf16_f32 v52, v26, v27
	v_cvt_pk_bf16_f32 v53, v28, v29
	v_cvt_pk_bf16_f32 v54, v30, v31
	v_cvt_pk_bf16_f32 v55, v32, v33
	v_cndmask_b32_e64 v7, v2, v5, s[80:81]
	v_lshlrev_b32_e32 v7, s82, v7
	global_store_dwordx4 v7, v[52:55], s[78:79]
	s_waitcnt vmcnt(3)
	v_mul_f32_e32 v34, s52, v34
	v_mul_f32_e32 v35, s53, v35
	v_mul_f32_e32 v36, s54, v36
	v_mul_f32_e32 v37, s55, v37
	v_mul_f32_e32 v38, s56, v38
	v_mul_f32_e32 v39, s57, v39
	v_mul_f32_e32 v40, s58, v40
	v_mul_f32_e32 v41, s59, v41
	v_cvt_pk_bf16_f32 v56, v34, v35
	v_cvt_pk_bf16_f32 v57, v36, v37
	v_cvt_pk_bf16_f32 v58, v38, v39
	v_cvt_pk_bf16_f32 v59, v40, v41
	v_cndmask_b32_e64 v7, v2, v5, s[92:93]
	v_lshlrev_b32_e32 v7, s94, v7
	global_store_dwordx4 v7, v[56:59], s[90:91]
	s_add_u32 s84, s84, 1
	s_lshl_b32 s0, s84, 2
	s_mul_i32 s0, s0, s86
	s_add_u32 s0, s0, s2
	s_cmp_lt_u32 s0, 6480
	s_cbranch_scc1 .Lpa_loop
	v_writelane_b32 v254, s86, 40
	s_nop 1
	v_writelane_b32 v254, s87, 41

	.amdhsa_kernel _Z14fwd_megakernel6Params
		.amdhsa_group_segment_fixed_size 0
		.amdhsa_private_segment_fixed_size 0
		.amdhsa_kernarg_size 456
		.amdhsa_user_sgpr_count 2
		.amdhsa_user_sgpr_dispatch_ptr 0
		.amdhsa_user_sgpr_queue_ptr 0
		.amdhsa_user_sgpr_kernarg_segment_ptr 1
		.amdhsa_user_sgpr_dispatch_id 0
		.amdhsa_user_sgpr_kernarg_preload_length 0
		.amdhsa_user_sgpr_kernarg_preload_offset 0
		.amdhsa_user_sgpr_private_segment_size 0
		.amdhsa_uses_dynamic_stack 0
		.amdhsa_enable_private_segment 0
		.amdhsa_system_sgpr_workgroup_id_x 1
		.amdhsa_system_sgpr_workgroup_id_y 0
		.amdhsa_system_sgpr_workgroup_id_z 0
		.amdhsa_system_sgpr_workgroup_info 0
		.amdhsa_system_vgpr_workitem_id 2
		.amdhsa_next_free_vgpr 255
		.amdhsa_next_free_sgpr 102
		.amdhsa_accum_offset 256
		.amdhsa_reserve_vcc 1
		.amdhsa_float_round_mode_32 0
		.amdhsa_float_round_mode_16_64 0
		.amdhsa_float_denorm_mode_32 3
		.amdhsa_float_denorm_mode_16_64 3
		.amdhsa_dx10_clamp 1
		.amdhsa_ieee_mode 1
		.amdhsa_fp16_overflow 0
		.amdhsa_tg_split 0
		.amdhsa_exception_fp_ieee_invalid_op 0
		.amdhsa_exception_fp_denorm_src 0
		.amdhsa_exception_fp_ieee_div_zero 0
		.amdhsa_exception_fp_ieee_overflow 0
		.amdhsa_exception_fp_ieee_underflow 0
		.amdhsa_exception_fp_ieee_inexact 0
		.amdhsa_exception_int_div_zero 0
	.end_amdhsa_kernel

amdhsa.kernels:
  - .agpr_count:     0
    .args:
      - .offset:         0
        .size:           200
        .value_kind:     by_value
      - .offset:         200
        .size:           4
        .value_kind:     hidden_block_count_x
      - .offset:         204
        .size:           4
        .value_kind:     hidden_block_count_y
      - .offset:         208
        .size:           4
        .value_kind:     hidden_block_count_z
      - .offset:         212
        .size:           2
        .value_kind:     hidden_group_size_x
      - .offset:         214
        .size:           2
        .value_kind:     hidden_group_size_y
      - .offset:         216
        .size:           2
        .value_kind:     hidden_group_size_z
      - .offset:         218
        .size:           2
        .value_kind:     hidden_remainder_x
      - .offset:         220
        .size:           2
        .value_kind:     hidden_remainder_y
      - .offset:         222
        .size:           2
        .value_kind:     hidden_remainder_z
      - .offset:         240
        .size:           8
        .value_kind:     hidden_global_offset_x
      - .offset:         248
        .size:           8
        .value_kind:     hidden_global_offset_y
      - .offset:         256
        .size:           8
        .value_kind:     hidden_global_offset_z
      - .offset:         264
        .size:           2
        .value_kind:     hidden_grid_dims
      - .offset:         288
        .size:           8
        .value_kind:     hidden_multigrid_sync_arg
      - .offset:         320
        .size:           4
        .value_kind:     hidden_dynamic_lds_size
    .group_segment_fixed_size: 0
    .kernarg_segment_align: 8
    .kernarg_segment_size: 456
    .language:       OpenCL C
    .language_version:
      - 2
      - 0
    .max_flat_workgroup_size: 512
    .name:           _Z14fwd_megakernel6Params
    .private_segment_fixed_size: 0
    .sgpr_count:     108
    .sgpr_spill_count: 63
    .symbol:         _Z14fwd_megakernel6Params.kd
    .uniform_work_group_size: 1
    .uses_dynamic_stack: false
    .vgpr_count:     255
    .vgpr_spill_count: 0
    .wavefront_size: 64
